# mask variant + first-block PV MFMAs take srcC=0 (the 0*alpha accumulator init: 1 exp, 1 mul, 15 v_mov, 8 v_mov_b64 per query set dropped)
# speedup vs baseline: 1.0042x; 1.0007x over previous
; __device__ __forceinline__ unsigned pk2(float lo, float hi) { return pg8::cvt_pk_bf16(lo, hi); }
; __device__ __forceinline__ void att_block(const bf16x8 (&kf)[4], const bf16x8 (&qf)[4], const bf16x8 (&va)[4], f32x16& o0, f32x16& o1, float& mrun, float& lrun, bool domask, int lo_, int hi_) {
;     f32x16 st;
; #pragma unroll
;     for (int i = 0; i < 16; ++i) st[i] = 0.f;
; #pragma unroll
;     for (int kk = 0; kk < 4; ++kk) st = __builtin_amdgcn_mfma_f32_32x32x16_bf16(kf[kk], qf[kk], st, 0, 0, 0);
;     if (domask) {
;         asm volatile("" : "+v"(lo_), "+v"(hi_));
; #pragma unroll
;         for (int i = 0; i < 16; ++i) { const int ci = (i & 3) + 8 * (i >> 2); st[i] = ((ci - lo_) | (hi_ - ci)) < 0 ? -INFINITY : st[i]; }
;     }
;     float bmax = -INFINITY;
; #pragma unroll
;     for (int i = 0; i < 16; ++i) bmax = fmaxf(bmax, st[i]);
;     bmax = fmaxf(bmax, __shfl_xor(bmax, 32));
;     const float mnew = fmaxf(mrun, bmax);
;     float lsum = 0.f;
; #pragma unroll
;     for (int i = 0; i < 16; ++i) { st[i] = __builtin_amdgcn_exp2f(st[i] - mnew); lsum += st[i]; }
;     lsum += __shfl_xor(lsum, 32);
;     const float alpha = __builtin_amdgcn_exp2f(mrun - mnew);
;     lrun = lrun * alpha + lsum; mrun = mnew;
; #pragma unroll
;     for (int i = 0; i < 16; ++i) { o0[i] *= alpha; o1[i] *= alpha; }
; #pragma unroll
;     for (int s = 0; s < 2; ++s) { v4u w; w.x = pk2(st[8 * s], st[8 * s + 1]); w.y = pk2(st[8 * s + 2], st[8 * s + 3]); w.z = pk2(st[8 * s + 4], st[8 * s + 5]); w.w = pk2(st[8 * s + 6], st[8 * s + 7]);
;         const bf16x8 pb = __builtin_bit_cast(bf16x8, w);
;         o0 = __builtin_amdgcn_mfma_f32_32x32x16_bf16(va[2 * s], pb, o0, 0, 0, 0);
;         o1 = __builtin_amdgcn_mfma_f32_32x32x16_bf16(va[2 * s + 1], pb, o1, 0, 0, 0); }
.LBB0_80:
	v_add_u32_e32 v0, 0xffffffa0, v191
	v_mul_lo_u32 v0, s56, v0
	v_add_u32_e32 v4, s11, v0
	v_max_i32_e32 v164, 0, v4
	v_lshl_add_u64 v[0:1], s[12:13], 0, v[164:165]
	v_lshlrev_b64 v[0:1], 7, v[0:1]
	s_add_i32 s57, s33, 0x1000
	s_lshl_b32 s6, s56, 3
	s_waitcnt vmcnt(0)
	v_lshl_add_u64 v[2:3], v[180:181], 0, v[0:1]
	s_mov_b32 m0, s57
	s_add_i32 s7, s33, 0x3000
	v_add_u32_e32 v4, s6, v4
	global_load_lds_dwordx4 v[2:3], off
	v_lshl_add_u64 v[0:1], v[182:183], 0, v[0:1]
	s_mov_b32 m0, s7
	v_max_i32_e32 v164, 0, v4
	global_load_lds_dwordx4 v[0:1], off
	v_lshl_add_u64 v[0:1], s[12:13], 0, v[164:165]
	v_lshlrev_b64 v[0:1], 7, v[0:1]
	v_readlane_b32 s15, v254, 28
	v_lshl_add_u64 v[2:3], v[180:181], 0, v[0:1]
	s_mov_b32 m0, s15
	v_readlane_b32 s15, v254, 29
	v_add_u32_e32 v4, s6, v4
	global_load_lds_dwordx4 v[2:3], off
	v_lshl_add_u64 v[0:1], v[182:183], 0, v[0:1]
	s_mov_b32 m0, s15
	v_max_i32_e32 v164, 0, v4
	global_load_lds_dwordx4 v[0:1], off
	v_lshl_add_u64 v[0:1], s[12:13], 0, v[164:165]
	v_lshlrev_b64 v[0:1], 7, v[0:1]
	s_add_i32 s15, s33, 0x1800
	v_lshl_add_u64 v[2:3], v[180:181], 0, v[0:1]
	s_mov_b32 m0, s15
	s_add_i32 s17, s33, 0x3800
	v_add_u32_e32 v51, s6, v4
	global_load_lds_dwordx4 v[2:3], off
	v_lshl_add_u64 v[0:1], v[182:183], 0, v[0:1]
	s_mov_b32 m0, s17
	v_max_i32_e32 v164, 0, v51
	global_load_lds_dwordx4 v[0:1], off
	v_lshl_add_u64 v[0:1], s[12:13], 0, v[164:165]
	v_lshlrev_b64 v[0:1], 7, v[0:1]
	s_add_i32 s21, s33, 0x1c00
	v_lshl_add_u64 v[2:3], v[180:181], 0, v[0:1]
	s_mov_b32 m0, s21
	v_readlane_b32 s59, v254, 30
	global_load_lds_dwordx4 v[2:3], off
	v_lshl_add_u64 v[0:1], v[182:183], 0, v[0:1]
	s_mov_b32 m0, s59
	v_max_i32_e32 v199, s58, v189
	global_load_lds_dwordx4 v[0:1], off
	ds_read_b128 v[0:3], v225
	ds_read_b128 v[16:19], v226
	s_waitcnt vmcnt(0) lgkmcnt(0)
	v_mfma_f32_32x32x16_bf16 v[0:15], v[0:3], v[128:131], 0
	ds_read_b128 v[20:23], v228
	s_mov_b32 s59, 0xff800000
	v_mfma_f32_32x32x16_bf16 v[0:15], v[16:19], v[124:127], v[0:15]
	ds_read_b128 v[16:19], v227
	ds_read_b64_tr_b16 v[34:35], v229 offset:8192
	ds_read_b64_tr_b16 v[36:37], v229 offset:9216
	ds_read_b64_tr_b16 v[40:41], v229 offset:9280
	ds_read_b64_tr_b16 v[38:39], v229 offset:8256
	ds_read_b64_tr_b16 v[42:43], v229 offset:10240
	ds_read_b64_tr_b16 v[44:45], v229 offset:11264
	ds_read_b64_tr_b16 v[48:49], v229 offset:11328
	ds_read_b64_tr_b16 v[46:47], v229 offset:10304
	s_waitcnt lgkmcnt(8)
	v_mfma_f32_32x32x16_bf16 v[0:15], v[16:19], v[120:123], v[0:15]
	v_sub_u32_e32 v16, v199, v193
	v_mov_b32_e32 v17, v214
	s_waitcnt lgkmcnt(0)
	s_nop 0
	v_mfma_f32_32x32x16_bf16 v[0:15], v[20:23], v[116:119], v[0:15]
	s_nop 6
	v_cmp_ge_i32_e32 vcc, 0, v16
	v_cmp_ge_i32_e64 s[24:25], 1, v16
	v_cmp_ge_i32_e64 s[26:27], 2, v16
	v_cmp_ge_i32_e64 s[28:29], 3, v16
	v_cmp_ge_i32_e64 s[30:31], 8, v16
	v_cmp_ge_i32_e64 s[34:35], 9, v16
	v_cndmask_b32_e32 v0, v211, v0, vcc
	v_cmp_ge_i32_e32 vcc, 10, v16
	v_cndmask_b32_e64 v1, v211, v1, s[24:25]
	v_cmp_ge_i32_e64 s[24:25], 11, v16
	v_cndmask_b32_e64 v2, v211, v2, s[26:27]
	v_cmp_ge_i32_e64 s[26:27], 16, v16
	v_cndmask_b32_e64 v3, v211, v3, s[28:29]
	v_cmp_ge_i32_e64 s[28:29], 17, v16
	v_cndmask_b32_e64 v4, v211, v4, s[30:31]
	v_cmp_ge_i32_e64 s[30:31], 18, v16
	v_cndmask_b32_e64 v5, v211, v5, s[34:35]
	v_cmp_ge_i32_e64 s[34:35], 19, v16
	v_cndmask_b32_e32 v6, v211, v6, vcc
	v_cmp_ge_i32_e32 vcc, 24, v16
	v_cndmask_b32_e64 v7, v211, v7, s[24:25]
	v_cmp_ge_i32_e64 s[24:25], 25, v16
	v_cndmask_b32_e64 v8, v211, v8, s[26:27]
	v_cmp_ge_i32_e64 s[26:27], 26, v16
	v_cndmask_b32_e64 v9, v211, v9, s[28:29]
	v_cmp_ge_i32_e64 s[28:29], 27, v16
	v_cndmask_b32_e64 v10, v211, v10, s[30:31]
	v_cndmask_b32_e64 v11, v211, v11, s[34:35]
	v_cndmask_b32_e32 v56, v211, v12, vcc
	v_cndmask_b32_e64 v57, v211, v13, s[24:25]
	v_cndmask_b32_e64 v58, v211, v14, s[26:27]
	v_cndmask_b32_e64 v59, v211, v15, s[28:29]
	s_nop 0
	s_nop 0
	v_max3_f32 v12, v0, s59, v1
	v_max3_f32 v12, v12, v2, v3
	v_max3_f32 v12, v12, v4, v5
	v_max3_f32 v12, v12, v6, v7
	v_max3_f32 v12, v12, v8, v9
	v_xor_b32_e32 v13, 32, v206
	v_max3_f32 v12, v12, v10, v11
	v_cmp_lt_i32_e32 vcc, v13, v208
	v_max3_f32 v12, v12, v56, v57
	v_max3_f32 v12, v12, v58, v59
	v_cndmask_b32_e32 v13, v206, v13, vcc
	v_lshlrev_b32_e32 v201, 2, v13
	ds_bpermute_b32 v13, v201, v12
	s_mov_b32 s59, 0xf149f2ca
	s_waitcnt lgkmcnt(0)
	v_max3_f32 v50, v12, v13, s59
	v_sub_f32_e32 v0, v0, v50
	v_exp_f32_e32 v16, v0
	v_sub_f32_e32 v0, v1, v50
	v_exp_f32_e32 v17, v0
	v_sub_f32_e32 v1, v2, v50
	v_exp_f32_e32 v18, v1
	v_sub_f32_e32 v1, v3, v50
	v_exp_f32_e32 v19, v1
	v_sub_f32_e32 v1, v4, v50
	v_add_f32_e32 v0, 0, v16
	v_exp_f32_e32 v20, v1
	v_sub_f32_e32 v1, v5, v50
	v_add_f32_e32 v0, v17, v0
	v_exp_f32_e32 v21, v1
	v_sub_f32_e32 v1, v6, v50
	v_add_f32_e32 v0, v18, v0
	v_exp_f32_e32 v22, v1
	v_sub_f32_e32 v1, v7, v50
	v_add_f32_e32 v0, v19, v0
	v_exp_f32_e32 v23, v1
	v_sub_f32_e32 v1, v8, v50
	v_add_f32_e32 v0, v20, v0
	v_exp_f32_e32 v60, v1
	v_sub_f32_e32 v1, v9, v50
	v_add_f32_e32 v0, v21, v0
	v_exp_f32_e32 v61, v1
	v_add_f32_e32 v0, v22, v0
	v_add_f32_e32 v0, v23, v0
	v_add_f32_e32 v0, v60, v0
	v_add_f32_e32 v62, v61, v0
	v_sub_f32_e32 v1, v10, v50
	v_cvt_pk_bf16_f32 v52, v16, v17
	v_sub_f32_e32 v16, v56, v50
	v_mov_b32_e32 v0, 0
	v_exp_f32_e32 v63, v1
	v_sub_f32_e32 v64, v11, v50
	v_cvt_pk_bf16_f32 v53, v18, v19
	v_cvt_pk_bf16_f32 v54, v20, v21
	v_cvt_pk_bf16_f32 v55, v22, v23
	v_exp_f32_e32 v56, v16
	v_sub_f32_e32 v16, v57, v50
	v_mfma_f32_32x32x16_bf16 v[18:33], v[34:37], v[52:55], 0
	v_exp_f32_e32 v57, v16
	v_sub_f32_e32 v34, v58, v50
	v_exp_f32_e32 v64, v64
	v_cvt_pk_bf16_f32 v36, v56, v57
	s_nop 1
	v_exp_f32_e32 v1, v34
	v_sub_f32_e32 v34, v59, v50
	v_mfma_f32_32x32x16_bf16 v[2:17], v[38:41], v[52:55], 0
	v_exp_f32_e32 v38, v34
	v_add_f32_e32 v39, v63, v62
	v_add_f32_e32 v39, v64, v39
	v_cvt_pk_bf16_f32 v34, v60, v61
	v_cvt_pk_bf16_f32 v35, v63, v64
	v_cvt_pk_bf16_f32 v37, v1, v38
	v_add_f32_e32 v39, v56, v39
	v_add_f32_e32 v39, v57, v39
	v_mfma_f32_32x32x16_bf16 v[18:33], v[42:45], v[34:37], v[18:33]
	v_add_f32_e32 v1, v1, v39
	v_add_f32_e32 v1, v38, v1
	ds_bpermute_b32 v232, v201, v1
	v_mfma_f32_32x32x16_bf16 v[2:17], v[46:49], v[34:37], v[2:17]
	v_add_u32_e32 v38, s6, v51
	v_max_i32_e32 v164, 0, v38
	v_lshl_add_u64 v[34:35], s[12:13], 0, v[164:165]
	v_lshlrev_b64 v[34:35], 7, v[34:35]
	s_mov_b32 m0, s33
	s_waitcnt vmcnt(0)
; #define LAS __attribute__((address_space(3)))
; __device__ __forceinline__ void att_block(const bf16x8 (&kf)[4], const bf16x8 (&qf)[4], const bf16x8 (&va)[4], f32x16& o0, f32x16& o1, float& mrun, float& lrun, bool domask, int lo_, int hi_) {
;     ...
;     if (domask) {
;         asm volatile("" : "+v"(lo_), "+v"(hi_));
; #pragma unroll
;         for (int i = 0; i < 16; ++i) { const int ci = (i & 3) + 8 * (i >> 2); st[i] = ((ci - lo_) | (hi_ - ci)) < 0 ? -INFINITY : st[i]; }
;     }
;     float bmax = -INFINITY;
; #pragma unroll
;     for (int i = 0; i < 16; ++i) bmax = fmaxf(bmax, st[i]);
;     bmax = fmaxf(bmax, __shfl_xor(bmax, 32));
;     const float mnew = fmaxf(mrun, bmax);
;     float lsum = 0.f;
; #pragma unroll
;     for (int i = 0; i < 16; ++i) { st[i] = __builtin_amdgcn_exp2f(st[i] - mnew); lsum += st[i]; }
;     lsum += __shfl_xor(lsum, 32);
;     const float alpha = __builtin_amdgcn_exp2f(mrun - mnew);
;     lrun = lrun * alpha + lsum; mrun = mnew;
; #pragma unroll
;     for (int i = 0; i < 16; ++i) { o0[i] *= alpha; o1[i] *= alpha; }
; #pragma unroll
; __device__ __forceinline__ void att_phase(unsigned char* ws, LAS unsigned char* lds, int lane, int wave, int G) {
;     ...
;         for (int kb = 0; kb < 6; ++kb) {
;             asm volatile("s_waitcnt vmcnt(0)" ::: "memory");
;             if (kb < 5) ATT_DMA_KV(P, kb + 1, sb ^ 1);
;             else if (hn) ATT_DMA_KV(N, 0, sb ^ 1);
;             bf16x8 kf[4], va[4];
; #pragma unroll
;             for (int kk = 0; kk < 4; ++kk) kf[kk] = *(LAS const bf16x8*)(kfb + sb * 4096 + (((2 * kk + h) ^ (qc & 7)) << 4));
;             LAS const unsigned char* trs = trb + 8192 + sb * 4096;
; #pragma unroll
;             for (int s = 0; s < 2; ++s) {
;                 const s16x4 lo0 = vtr(trs + (16 * s) * VP), hi0 = vtr(trs + (16 * s + 8) * VP);
;                 const s16x4 lo1 = vtr(trs + (16 * s) * VP + 64), hi1 = vtr(trs + (16 * s + 8) * VP + 64);
;                 va[2 * s] = (bf16x8){lo0[0], lo0[1], lo0[2], lo0[3], hi0[0], hi0[1], hi0[2], hi0[3]};
;                 va[2 * s + 1] = (bf16x8){lo1[0], lo1[1], lo1[2], lo1[3], hi1[0], hi1[1], hi1[2], hi1[3]};
;             }
;             if (kb <= 4) {
;                 att_block(kf, qfA, va, oA0, oA1, mA, lA, kb == 0 || kb == 4 || kminA > 32 * kb, mloA - 4 * h - 32 * kb, qc + 128 - 4 * h - 32 * kb);
	v_lshl_add_u64 v[36:37], v[180:181], 0, v[34:35]
	v_add_u32_e32 v38, s6, v38
	global_load_lds_dwordx4 v[36:37], off
	v_lshl_add_u64 v[34:35], v[182:183], 0, v[34:35]
	s_mov_b32 m0, s44
	v_max_i32_e32 v164, 0, v38
	global_load_lds_dwordx4 v[34:35], off
	v_lshl_add_u64 v[34:35], s[12:13], 0, v[164:165]
	v_lshlrev_b64 v[34:35], 7, v[34:35]
	v_lshl_add_u64 v[36:37], v[180:181], 0, v[34:35]
	s_mov_b32 m0, s66
	v_add_u32_e32 v38, s6, v38
	global_load_lds_dwordx4 v[36:37], off
	v_lshl_add_u64 v[34:35], v[182:183], 0, v[34:35]
	s_mov_b32 m0, s67
	v_max_i32_e32 v164, 0, v38
	global_load_lds_dwordx4 v[34:35], off
	v_lshl_add_u64 v[34:35], s[12:13], 0, v[164:165]
	v_lshlrev_b64 v[34:35], 7, v[34:35]
	v_lshl_add_u64 v[36:37], v[180:181], 0, v[34:35]
	s_mov_b32 m0, s48
	v_lshl_add_u64 v[34:35], v[182:183], 0, v[34:35]
	global_load_lds_dwordx4 v[36:37], off
	s_mov_b32 m0, s49
	v_readlane_b32 s59, v254, 27
	global_load_lds_dwordx4 v[34:35], off
	v_add_u32_e32 v34, s6, v38
	v_max_i32_e32 v164, 0, v34
	v_lshl_add_u64 v[34:35], s[12:13], 0, v[164:165]
	v_lshlrev_b64 v[34:35], 7, v[34:35]
	v_lshl_add_u64 v[36:37], v[180:181], 0, v[34:35]
	s_mov_b32 m0, s72
	v_lshl_add_u64 v[34:35], v[182:183], 0, v[34:35]
	global_load_lds_dwordx4 v[36:37], off
	s_mov_b32 m0, s59
	s_cmp_gt_i32 s58, 32
	global_load_lds_dwordx4 v[34:35], off
	ds_read_b128 v[68:71], v225 offset:4096
	ds_read_b128 v[64:67], v226 offset:4096
	s_waitcnt lgkmcnt(0)
	v_mfma_f32_32x32x16_bf16 v[34:49], v[68:71], v[128:131], 0
	ds_read_b128 v[60:63], v227 offset:4096
	ds_read_b128 v[56:59], v228 offset:4096
	s_waitcnt vmcnt(0)
	ds_read_b64_tr_b16 v[52:53], v229 offset:12288
	ds_read_b64_tr_b16 v[54:55], v229 offset:13312
	ds_read_b64_tr_b16 v[94:95], v229 offset:13376
	ds_read_b64_tr_b16 v[92:93], v229 offset:12352
	ds_read_b64_tr_b16 v[88:89], v229 offset:14336
	ds_read_b64_tr_b16 v[90:91], v229 offset:15360
	ds_read_b64_tr_b16 v[86:87], v229 offset:15424
	ds_read_b64_tr_b16 v[84:85], v229 offset:14400
	v_mfma_f32_32x32x16_bf16 v[34:49], v[64:67], v[124:127], v[34:49]
	s_waitcnt lgkmcnt(9)
	v_mfma_f32_32x32x16_bf16 v[34:49], v[60:63], v[120:123], v[34:49]
	s_waitcnt lgkmcnt(8)
	v_mfma_f32_32x32x16_bf16 v[34:49], v[56:59], v[116:119], v[34:49]
	s_cbranch_scc0 .LBB0_82
	v_sub_u32_e32 v51, v199, v215
	v_mov_b32_e32 v72, v216
	s_nop 0
	s_nop 1
	v_cmp_ge_i32_e32 vcc, 0, v51
	v_cmp_ge_i32_e64 s[24:25], 1, v51
	v_cmp_ge_i32_e64 s[26:27], 2, v51
	v_cmp_ge_i32_e64 s[28:29], 3, v51
	v_cmp_ge_i32_e64 s[30:31], 8, v51
	v_cmp_ge_i32_e64 s[34:35], 9, v51
	v_cndmask_b32_e32 v34, v211, v34, vcc
	v_cmp_ge_i32_e32 vcc, 10, v51
	v_cndmask_b32_e64 v35, v211, v35, s[24:25]
	v_cmp_ge_i32_e64 s[24:25], 11, v51
	v_cndmask_b32_e64 v36, v211, v36, s[26:27]
	v_cmp_ge_i32_e64 s[26:27], 16, v51
	v_cndmask_b32_e64 v37, v211, v37, s[28:29]
	v_cmp_ge_i32_e64 s[28:29], 17, v51
	v_cndmask_b32_e64 v38, v211, v38, s[30:31]
	v_cmp_ge_i32_e64 s[30:31], 18, v51
	v_cndmask_b32_e64 v39, v211, v39, s[34:35]
	v_cmp_ge_i32_e64 s[34:35], 19, v51
	v_cndmask_b32_e32 v40, v211, v40, vcc
	v_cmp_ge_i32_e32 vcc, 24, v51
	v_cndmask_b32_e64 v41, v211, v41, s[24:25]
	v_cmp_ge_i32_e64 s[24:25], 25, v51
	v_cndmask_b32_e64 v42, v211, v42, s[26:27]
	v_cmp_ge_i32_e64 s[26:27], 26, v51
	v_cndmask_b32_e64 v43, v211, v43, s[28:29]
	v_cmp_ge_i32_e64 s[28:29], 27, v51
	v_cndmask_b32_e64 v44, v211, v44, s[30:31]
	v_cndmask_b32_e64 v45, v211, v45, s[34:35]
	v_cndmask_b32_e32 v46, v211, v46, vcc
	v_cndmask_b32_e64 v47, v211, v47, s[24:25]
	v_cndmask_b32_e64 v48, v211, v48, s[26:27]
	v_cndmask_b32_e64 v49, v211, v49, s[28:29]
	s_nop 0
	s_nop 1
.LBB0_82:
	s_mov_b32 s59, 0xff800000
	s_nop 9
	v_max3_f32 v51, v34, s59, v35
	v_max3_f32 v51, v51, v36, v37
	v_max3_f32 v51, v51, v38, v39
	v_max3_f32 v51, v51, v40, v41
	v_max3_f32 v51, v51, v42, v43
	v_max3_f32 v51, v51, v44, v45
	v_max3_f32 v51, v51, v46, v47
	v_max3_f32 v51, v51, v48, v49
	ds_bpermute_b32 v72, v201, v51
	v_max_i32_e32 v237, s14, v189
	s_mov_b32 s60, 0xff800000
	s_waitcnt lgkmcnt(0)
	v_max3_f32 v148, v50, v51, v72
	v_sub_f32_e32 v34, v34, v148
	v_exp_f32_e32 v72, v34
	v_sub_f32_e32 v35, v35, v148
	v_exp_f32_e32 v73, v35
	v_sub_f32_e32 v35, v36, v148
	v_exp_f32_e32 v74, v35
	v_sub_f32_e32 v35, v37, v148
	v_exp_f32_e32 v75, v35
	v_sub_f32_e32 v35, v38, v148
	v_add_f32_e32 v34, 0, v72
	v_exp_f32_e32 v76, v35
	v_sub_f32_e32 v35, v39, v148
	v_add_f32_e32 v34, v73, v34
	v_exp_f32_e32 v77, v35
	v_sub_f32_e32 v35, v40, v148
	v_add_f32_e32 v34, v74, v34
	v_exp_f32_e32 v78, v35
	v_sub_f32_e32 v35, v41, v148
	v_add_f32_e32 v34, v75, v34
	v_exp_f32_e32 v79, v35
	v_sub_f32_e32 v35, v42, v148
	v_add_f32_e32 v34, v76, v34
	v_exp_f32_e32 v80, v35
	v_sub_f32_e32 v35, v43, v148
	v_add_f32_e32 v34, v77, v34
	v_exp_f32_e32 v81, v35
	v_sub_f32_e32 v35, v44, v148
	v_add_f32_e32 v34, v78, v34
	v_exp_f32_e32 v82, v35
	v_sub_f32_e32 v35, v45, v148
	v_add_f32_e32 v34, v79, v34
	v_exp_f32_e32 v83, v35
	v_sub_f32_e32 v35, v46, v148
	v_add_f32_e32 v34, v80, v34
	v_exp_f32_e32 v96, v35
	v_sub_f32_e32 v35, v47, v148
	v_add_f32_e32 v34, v81, v34
	v_exp_f32_e32 v97, v35
	v_sub_f32_e32 v35, v48, v148
	v_add_f32_e32 v34, v82, v34
	v_exp_f32_e32 v98, v35
	v_sub_f32_e32 v35, v49, v148
	v_add_f32_e32 v34, v83, v34
	v_exp_f32_e32 v99, v35
	v_add_f32_e32 v34, v96, v34
	v_add_f32_e32 v34, v97, v34
	v_add_f32_e32 v34, v98, v34
	v_add_f32_e32 v235, v99, v34
	v_sub_f32_e32 v34, v50, v148
	v_exp_f32_e32 v188, v34
	ds_bpermute_b32 v236, v201, v235
	v_pk_mul_f32 v[34:35], v[32:33], v[188:189] op_sel_hi:[1,0]
	v_pk_mul_f32 v[32:33], v[30:31], v[188:189] op_sel_hi:[1,0]
	v_pk_mul_f32 v[30:31], v[28:29], v[188:189] op_sel_hi:[1,0]
	v_pk_mul_f32 v[28:29], v[26:27], v[188:189] op_sel_hi:[1,0]
	v_pk_mul_f32 v[26:27], v[24:25], v[188:189] op_sel_hi:[1,0]
	v_pk_mul_f32 v[24:25], v[22:23], v[188:189] op_sel_hi:[1,0]
	v_pk_mul_f32 v[22:23], v[20:21], v[188:189] op_sel_hi:[1,0]
	v_pk_mul_f32 v[20:21], v[18:19], v[188:189] op_sel_hi:[1,0]
	v_pk_mul_f32 v[50:51], v[16:17], v[188:189] op_sel_hi:[1,0]
	v_pk_mul_f32 v[48:49], v[14:15], v[188:189] op_sel_hi:[1,0]
	v_pk_mul_f32 v[46:47], v[12:13], v[188:189] op_sel_hi:[1,0]
	v_pk_mul_f32 v[44:45], v[10:11], v[188:189] op_sel_hi:[1,0]
	v_pk_mul_f32 v[42:43], v[8:9], v[188:189] op_sel_hi:[1,0]
	v_pk_mul_f32 v[40:41], v[6:7], v[188:189] op_sel_hi:[1,0]
	v_pk_mul_f32 v[38:39], v[4:5], v[188:189] op_sel_hi:[1,0]
	v_pk_mul_f32 v[36:37], v[2:3], v[188:189] op_sel_hi:[1,0]
	v_cvt_pk_bf16_f32 v2, v72, v73
	v_cvt_pk_bf16_f32 v3, v74, v75
	v_cvt_pk_bf16_f32 v4, v76, v77
	v_cvt_pk_bf16_f32 v5, v78, v79
	v_sub_u32_e32 v18, v237, v193
	v_mov_b32_e32 v19, v214
	v_mfma_f32_32x32x16_bf16 v[20:35], v[52:55], v[2:5], v[20:35]
	s_waitcnt lgkmcnt(0)
; __device__ __forceinline__ unsigned pk2(float lo, float hi) { return pg8::cvt_pk_bf16(lo, hi); }
; __device__ __forceinline__ void att_block(const bf16x8 (&kf)[4], const bf16x8 (&qf)[4], const bf16x8 (&va)[4], f32x16& o0, f32x16& o1, float& mrun, float& lrun, bool domask, int lo_, int hi_) {
;     ...
;     const float mnew = fmaxf(mrun, bmax);
;     float lsum = 0.f;
; #pragma unroll
;     for (int i = 0; i < 16; ++i) { st[i] = __builtin_amdgcn_exp2f(st[i] - mnew); lsum += st[i]; }
;     lsum += __shfl_xor(lsum, 32);
;     const float alpha = __builtin_amdgcn_exp2f(mrun - mnew);
;     lrun = lrun * alpha + lsum; mrun = mnew;
; #pragma unroll
;     for (int i = 0; i < 16; ++i) { o0[i] *= alpha; o1[i] *= alpha; }
; #pragma unroll
;     for (int s = 0; s < 2; ++s) { v4u w; w.x = pk2(st[8 * s], st[8 * s + 1]); w.y = pk2(st[8 * s + 2], st[8 * s + 3]); w.z = pk2(st[8 * s + 4], st[8 * s + 5]); w.w = pk2(st[8 * s + 6], st[8 * s + 7]);
;         const bf16x8 pb = __builtin_bit_cast(bf16x8, w);
;         o0 = __builtin_amdgcn_mfma_f32_32x32x16_bf16(va[2 * s], pb, o0, 0, 0, 0);
;         o1 = __builtin_amdgcn_mfma_f32_32x32x16_bf16(va[2 * s + 1], pb, o1, 0, 0, 0); }
	v_mfma_f32_32x32x16_bf16 v[36:51], v[92:95], v[2:5], v[36:51]
	v_cvt_pk_bf16_f32 v2, v80, v81
	v_cvt_pk_bf16_f32 v3, v82, v83
	v_cvt_pk_bf16_f32 v4, v96, v97
	v_cvt_pk_bf16_f32 v5, v98, v99
	s_nop 1
	v_mfma_f32_32x32x16_bf16 v[20:35], v[88:91], v[2:5], v[20:35]
	v_mfma_f32_32x32x16_bf16 v[36:51], v[84:87], v[2:5], v[36:51]
	v_mfma_f32_32x32x16_bf16 v[2:17], v[68:71], v[112:115], 0
	v_mfma_f32_32x32x16_bf16 v[2:17], v[64:67], v[108:111], v[2:17]
	v_mfma_f32_32x32x16_bf16 v[2:17], v[60:63], v[104:107], v[2:17]
	v_mfma_f32_32x32x16_bf16 v[2:17], v[56:59], v[100:103], v[2:17]
	s_nop 4
	v_cmp_ge_i32_e32 vcc, 0, v18
	v_cmp_ge_i32_e64 s[24:25], 1, v18
	v_cmp_ge_i32_e64 s[26:27], 2, v18
	v_cmp_ge_i32_e64 s[28:29], 3, v18
	v_cmp_ge_i32_e64 s[30:31], 8, v18
	v_cmp_ge_i32_e64 s[34:35], 9, v18
	s_nop 0
	v_cndmask_b32_e32 v2, v211, v2, vcc
	v_cmp_ge_i32_e32 vcc, 10, v18
	v_cndmask_b32_e64 v3, v211, v3, s[24:25]
	v_cmp_ge_i32_e64 s[24:25], 11, v18
	v_cndmask_b32_e64 v4, v211, v4, s[26:27]
	v_cmp_ge_i32_e64 s[26:27], 16, v18
	v_cndmask_b32_e64 v5, v211, v5, s[28:29]
	v_cmp_ge_i32_e64 s[28:29], 17, v18
	v_cndmask_b32_e64 v6, v211, v6, s[30:31]
	v_cmp_ge_i32_e64 s[30:31], 18, v18
	v_cndmask_b32_e64 v7, v211, v7, s[34:35]
	v_cmp_ge_i32_e64 s[34:35], 19, v18
	v_cndmask_b32_e32 v8, v211, v8, vcc
	v_cmp_ge_i32_e32 vcc, 24, v18
	v_cndmask_b32_e64 v9, v211, v9, s[24:25]
	v_cmp_ge_i32_e64 s[24:25], 25, v18
	v_cndmask_b32_e64 v10, v211, v10, s[26:27]
	v_cmp_ge_i32_e64 s[26:27], 26, v18
	v_cndmask_b32_e64 v11, v211, v11, s[28:29]
	v_cmp_ge_i32_e64 s[28:29], 27, v18
	v_cndmask_b32_e64 v12, v211, v12, s[30:31]
	v_cndmask_b32_e64 v13, v211, v13, s[34:35]
	v_cndmask_b32_e32 v14, v211, v14, vcc
	v_cndmask_b32_e64 v15, v211, v15, s[24:25]
	v_cndmask_b32_e64 v16, v211, v16, s[26:27]
	v_cndmask_b32_e64 v17, v211, v17, s[28:29]
	s_nop 0
	v_max3_f32 v18, v2, s59, v3
	v_max3_f32 v18, v18, v4, v5
	v_max3_f32 v18, v18, v6, v7
	v_max3_f32 v18, v18, v8, v9
	v_max3_f32 v18, v18, v10, v11
	v_max3_f32 v18, v18, v12, v13
	v_max3_f32 v18, v18, v14, v15
	v_max3_f32 v18, v18, v16, v17
	ds_bpermute_b32 v19, v201, v18
	s_mov_b32 s59, 0xf149f2ca
	s_waitcnt lgkmcnt(0)
	v_max3_f32 v150, v18, v19, s59
	v_sub_f32_e32 v2, v2, v150
	v_exp_f32_e32 v18, v2
	v_sub_f32_e32 v3, v3, v150
	v_exp_f32_e32 v19, v3
	v_sub_f32_e32 v3, v4, v150
	v_exp_f32_e32 v56, v3
	v_sub_f32_e32 v3, v5, v150
	v_exp_f32_e32 v57, v3
	v_sub_f32_e32 v3, v6, v150
	v_add_f32_e32 v2, 0, v18
	v_exp_f32_e32 v58, v3
	v_sub_f32_e32 v3, v7, v150
	v_add_f32_e32 v2, v19, v2
	v_exp_f32_e32 v59, v3
	v_sub_f32_e32 v3, v8, v150
	v_add_f32_e32 v2, v56, v2
	v_exp_f32_e32 v60, v3
	v_sub_f32_e32 v3, v9, v150
	v_add_f32_e32 v2, v57, v2
	v_exp_f32_e32 v61, v3
	v_sub_f32_e32 v3, v10, v150
	v_add_f32_e32 v2, v58, v2
	v_exp_f32_e32 v132, v3
	v_sub_f32_e32 v3, v11, v150
	v_add_f32_e32 v2, v59, v2
	v_exp_f32_e32 v133, v3
	v_sub_f32_e32 v3, v12, v150
	v_add_f32_e32 v2, v60, v2
	v_exp_f32_e32 v134, v3
	v_sub_f32_e32 v3, v13, v150
	v_add_f32_e32 v2, v61, v2
	v_exp_f32_e32 v135, v3
	v_sub_f32_e32 v3, v14, v150
	v_add_f32_e32 v2, v132, v2
	v_exp_f32_e32 v136, v3
	v_sub_f32_e32 v3, v15, v150
	v_add_f32_e32 v2, v133, v2
	v_exp_f32_e32 v137, v3
	v_sub_f32_e32 v3, v16, v150
	v_add_f32_e32 v2, v134, v2
	v_exp_f32_e32 v138, v3
	v_sub_f32_e32 v3, v17, v150
	v_add_f32_e32 v2, v135, v2
	v_exp_f32_e32 v139, v3
	v_add_f32_e32 v2, v136, v2
	v_add_f32_e32 v2, v137, v2
	v_add_f32_e32 v2, v138, v2
	v_add_f32_e32 v233, v139, v2
	v_cvt_pk_bf16_f32 v96, v18, v19
	v_cvt_pk_bf16_f32 v97, v56, v57
	v_cvt_pk_bf16_f32 v98, v58, v59
	v_mov_b32_e32 v2, 0
	v_cvt_pk_bf16_f32 v99, v60, v61
	ds_bpermute_b32 v234, v201, v233
	s_nop 0
	v_mfma_f32_32x32x16_bf16 v[68:83], v[52:55], v[96:99], 0
	v_cvt_pk_bf16_f32 v4, v132, v133
	v_cvt_pk_bf16_f32 v5, v134, v135
	v_mfma_f32_32x32x16_bf16 v[52:67], v[92:95], v[96:99], 0
	v_cvt_pk_bf16_f32 v6, v136, v137
	v_cvt_pk_bf16_f32 v7, v138, v139
	s_nop 1
	v_mfma_f32_32x32x16_bf16 v[68:83], v[88:91], v[4:7], v[68:83]
	v_mfma_f32_32x32x16_bf16 v[52:67], v[84:87], v[4:7], v[52:67]
	v_mul_lo_u32 v3, s56, v217
	v_add_u32_e32 v3, s11, v3
	v_max_i32_e32 v164, 0, v3
	v_lshl_add_u64 v[4:5], s[12:13], 0, v[164:165]
	v_lshlrev_b64 v[4:5], 7, v[4:5]
	s_mov_b32 m0, s57
	s_waitcnt vmcnt(0)
	v_lshl_add_u64 v[6:7], v[180:181], 0, v[4:5]
	v_add_u32_e32 v3, s6, v3
	global_load_lds_dwordx4 v[6:7], off
	v_lshl_add_u64 v[4:5], v[182:183], 0, v[4:5]
	s_mov_b32 m0, s7
	v_max_i32_e32 v164, 0, v3
	global_load_lds_dwordx4 v[4:5], off
	v_lshl_add_u64 v[4:5], s[12:13], 0, v[164:165]
	v_lshlrev_b64 v[4:5], 7, v[4:5]
	v_readlane_b32 s59, v254, 28
	v_lshl_add_u64 v[6:7], v[180:181], 0, v[4:5]
	s_mov_b32 m0, s59
	v_readlane_b32 s59, v254, 29
	v_add_u32_e32 v3, s6, v3
	global_load_lds_dwordx4 v[6:7], off
	v_lshl_add_u64 v[4:5], v[182:183], 0, v[4:5]
	s_mov_b32 m0, s59
	v_max_i32_e32 v164, 0, v3
	global_load_lds_dwordx4 v[4:5], off
	v_lshl_add_u64 v[4:5], s[12:13], 0, v[164:165]
	v_lshlrev_b64 v[4:5], 7, v[4:5]
	v_lshl_add_u64 v[6:7], v[180:181], 0, v[4:5]
	s_mov_b32 m0, s15
	v_add_u32_e32 v3, s6, v3
	global_load_lds_dwordx4 v[6:7], off
	v_lshl_add_u64 v[4:5], v[182:183], 0, v[4:5]
	s_mov_b32 m0, s17
	v_max_i32_e32 v164, 0, v3
	global_load_lds_dwordx4 v[4:5], off
	v_lshl_add_u64 v[4:5], s[12:13], 0, v[164:165]
	v_lshlrev_b64 v[4:5], 7, v[4:5]
	v_lshl_add_u64 v[6:7], v[180:181], 0, v[4:5]
	s_mov_b32 m0, s21
	v_readlane_b32 s59, v254, 30
	global_load_lds_dwordx4 v[6:7], off
	v_lshl_add_u64 v[4:5], v[182:183], 0, v[4:5]
	s_mov_b32 m0, s59
	s_cmpk_lt_i32 s58, 0x41
	global_load_lds_dwordx4 v[4:5], off
	ds_read_b128 v[144:147], v225
	ds_read_b128 v[140:143], v226
	s_waitcnt lgkmcnt(0)
	v_mfma_f32_32x32x16_bf16 v[4:19], v[144:147], v[128:131], 0
	ds_read_b128 v[136:139], v227
	ds_read_b128 v[132:135], v228
	s_waitcnt vmcnt(0)
	ds_read_b64_tr_b16 v[96:97], v229 offset:8192
	ds_read_b64_tr_b16 v[98:99], v229 offset:9216
	ds_read_b64_tr_b16 v[94:95], v229 offset:9280
	ds_read_b64_tr_b16 v[92:93], v229 offset:8256
	ds_read_b64_tr_b16 v[88:89], v229 offset:10240
	ds_read_b64_tr_b16 v[90:91], v229 offset:11264
	ds_read_b64_tr_b16 v[86:87], v229 offset:11328
	ds_read_b64_tr_b16 v[84:85], v229 offset:10304
	v_mfma_f32_32x32x16_bf16 v[4:19], v[140:143], v[124:127], v[4:19]
	s_waitcnt lgkmcnt(9)
	v_mfma_f32_32x32x16_bf16 v[4:19], v[136:139], v[120:123], v[4:19]
	s_waitcnt lgkmcnt(8)
	v_mfma_f32_32x32x16_bf16 v[4:19], v[132:135], v[116:119], v[4:19]
	s_cbranch_scc1 .LBB0_84
; __device__ __forceinline__ void att_block(const bf16x8 (&kf)[4], const bf16x8 (&qf)[4], const bf16x8 (&va)[4], f32x16& o0, f32x16& o1, float& mrun, float& lrun, bool domask, int lo_, int hi_) {
;     ...
;     if (domask) {
;         asm volatile("" : "+v"(lo_), "+v"(hi_));
; #pragma unroll
;         for (int i = 0; i < 16; ++i) { const int ci = (i & 3) + 8 * (i >> 2); st[i] = ((ci - lo_) | (hi_ - ci)) < 0 ? -INFINITY : st[i]; }
;     }
	v_sub_u32_e32 v3, v199, v218
	v_mov_b32_e32 v149, v219
	s_nop 0
	s_nop 1
	v_cmp_ge_i32_e32 vcc, 0, v3
	v_cmp_ge_i32_e64 s[24:25], 1, v3
	v_cmp_ge_i32_e64 s[26:27], 2, v3
	v_cmp_ge_i32_e64 s[28:29], 3, v3
	v_cmp_ge_i32_e64 s[30:31], 8, v3
	v_cmp_ge_i32_e64 s[34:35], 9, v3
	v_cndmask_b32_e32 v4, v211, v4, vcc
	v_cmp_ge_i32_e32 vcc, 10, v3
	v_cndmask_b32_e64 v5, v211, v5, s[24:25]
	v_cmp_ge_i32_e64 s[24:25], 11, v3
	v_cndmask_b32_e64 v6, v211, v6, s[26:27]
	v_cmp_ge_i32_e64 s[26:27], 16, v3
	v_cndmask_b32_e64 v7, v211, v7, s[28:29]
	v_cmp_ge_i32_e64 s[28:29], 17, v3
	v_cndmask_b32_e64 v8, v211, v8, s[30:31]
	v_cmp_ge_i32_e64 s[30:31], 18, v3
	v_cndmask_b32_e64 v9, v211, v9, s[34:35]
	v_cmp_ge_i32_e64 s[34:35], 19, v3
	v_cndmask_b32_e32 v10, v211, v10, vcc
	v_cmp_ge_i32_e32 vcc, 24, v3
	v_cndmask_b32_e64 v11, v211, v11, s[24:25]
	v_cmp_ge_i32_e64 s[24:25], 25, v3
	v_cndmask_b32_e64 v12, v211, v12, s[26:27]
	v_cmp_ge_i32_e64 s[26:27], 26, v3
	v_cndmask_b32_e64 v13, v211, v13, s[28:29]
	v_cmp_ge_i32_e64 s[28:29], 27, v3
	v_cndmask_b32_e64 v14, v211, v14, s[30:31]
	v_cndmask_b32_e64 v15, v211, v15, s[34:35]
	v_cndmask_b32_e32 v16, v211, v16, vcc
	v_cndmask_b32_e64 v17, v211, v17, s[24:25]
	v_cndmask_b32_e64 v18, v211, v18, s[26:27]
	v_cndmask_b32_e64 v19, v211, v19, s[28:29]
	s_nop 0
	s_nop 1
